# P1 third round (96 transposed-V units) moved into the P2 phase beside the light units; transposed unit order remapped
# speedup vs baseline: 1.0234x; 1.0234x over previous
; #define LAS __attribute__((address_space(3)))
; #define REPS(k) for (int rep_ = 0; rep_ < (((RPM) >> (k)) & 1) + 1; ++rep_)
; template <int MAPK>
; __device__ __forceinline__ void transpose_item(const float* W, int K, int N, int ND, bf16_t* WT, const float* g, LAS float* scr, int item, int lane) {
;     const int nblk = ND / 64, kb = item / nblk, nb = item % nblk, k0 = 64 * kb, n0 = 64 * nb;
;     const int c4 = (lane & 15) * 4, kr = lane >> 4;
;     int src = n0 + c4; if (MAPK == 1) src = inmap(src); if (MAPK == 2) src = upmap(src);
;     f32x4 vv[16];
; #pragma unroll
;     for (int i = 0; i < 16; ++i) { const int kk = 4 * i + kr;
;         vv[i] = (f32x4){0.f, 0.f, 0.f, 0.f};
;         if (src >= 0) vv[i] = *(const f32x4*)(W + (size_t)(k0 + kk) * N + src); }
; #pragma unroll
;     for (int i = 0; i < 16; ++i) { const int kk = 4 * i + kr; f32x4 v = vv[i];
;         if (g) v = v * g[k0 + kk];
;         scr[kk * 65 + c4] = v[0]; scr[kk * 65 + c4 + 1] = v[1]; scr[kk * 65 + c4 + 2] = v[2]; scr[kk * 65 + c4 + 3] = v[3]; }
; __global__ void __launch_bounds__(512, 2) hybrid_fwd(Params p) {
;     ...
;     if (PH(0)) REPS(0) { PHB
;         LAS float* scr = (LAS float*)(lds + wave * 16640);
;         const int gw = c * 8 + wave, NGW = G * 8;
;         constexpr int I_IN = 32 * (NWIN / 64), I_OUT = 32 * 32, I_Q = 32 * 8, I_KV = 32 * 16, I_O = 8 * 32, I_UP = 32 * 176, I_DN = 88 * 32;
;         constexpr int I_LAYER = I_IN + I_OUT + I_Q + I_KV + I_O + I_UP + I_DN;
;         for (int it = gw; it < 4 * I_LAYER; it += NGW) {
;             const int l = it / I_LAYER; int r = it % I_LAYER; unsigned char* wl = ws + WS_W + (size_t)l * SZ_LAYER;
;             if (r < I_IN) { transpose_item<1>(p.w_in + (size_t)l * D_ * INC, D_, INC, NWIN, (bf16_t*)(WL + OF_WIN), p.norm_mix + l * D_, scr, r, lane); continue; } r -= I_IN;
.LBB0_19:
	v_readlane_b32 s4, v255, 1
	s_nop 3
	s_cmp_eq_u32 s4, 0x100
	s_cselect_b32 s5, 1, 0
	s_movk_i32 s6, 0x200
	s_cselect_b32 s6, s6, 0x7fffffff
	s_mov_b32 s7, 0
	s_nop 0
	v_writelane_b32 v255, s5, 58
	v_writelane_b32 v255, s7, 59
	v_writelane_b32 v255, s6, 63
	s_load_dwordx16 s[52:67], s[0:1], 0x0
	s_load_dwordx16 s[12:27], s[0:1], 0x40
	s_andn2_b32 s10, s10, 63
	v_mbcnt_hi_u32_b32 v235, -1, v0
	v_add_u32_e32 v234, s10, v235
	v_mov_b32_e32 v72, v234
	s_waitcnt lgkmcnt(0)
	v_writelane_b32 v255, s12, 4
	s_mov_b64 s[4:5], s[50:51]
	s_nop 0
	v_writelane_b32 v255, s13, 5
	v_writelane_b32 v255, s14, 6
	v_writelane_b32 v255, s15, 7
	v_writelane_b32 v255, s16, 8
	v_writelane_b32 v255, s17, 9
	v_writelane_b32 v255, s18, 10
	v_writelane_b32 v255, s19, 11
	v_writelane_b32 v255, s20, 12
	v_writelane_b32 v255, s21, 13
	v_writelane_b32 v255, s22, 14
	v_writelane_b32 v255, s23, 15
	v_writelane_b32 v255, s24, 16
	v_writelane_b32 v255, s25, 17
	v_writelane_b32 v255, s26, 18
	v_writelane_b32 v255, s27, 19
	s_nop 0
	v_readlane_b32 s26, v255, 0
	v_readlane_b32 s27, v255, 1
	s_lshl_b32 s1, s26, 3
	v_readfirstlane_b32 s0, v72
	s_ashr_i32 s0, s0, 6
	v_and_b32_e32 v73, 63, v72
	s_add_i32 s6, s0, s1
	s_lshl_b32 s8, s27, 3
	s_cmp_gt_i32 s6, 0xc9ff
	v_lshlrev_b32_e32 v74, 2, v73
	s_cbranch_scc1 .LBB0_244
	s_cmp_lg_u64 s[36:37], 0
	s_cselect_b64 s[2:3], -1, 0
	v_writelane_b32 v255, s2, 20
	v_lshlrev_b32_e32 v0, 3, v73
	s_mulk_i32 s0, 0x4100
	v_writelane_b32 v255, s3, 21
	v_lshrrev_b32_e32 v84, 3, v73
	v_readlane_b32 s68, v255, 4
	v_readlane_b32 s76, v255, 12
	v_readlane_b32 s77, v255, 13
	v_readlane_b32 s74, v255, 10
	v_readlane_b32 s75, v255, 11
	s_cmp_lg_u64 s[76:77], 0
	v_readlane_b32 s72, v255, 8
	v_readlane_b32 s73, v255, 9
	s_cselect_b64 s[2:3], -1, 0
	s_cmp_lg_u64 s[74:75], 0
	s_cselect_b64 s[14:15], -1, 0
	s_cmp_lg_u64 s[72:73], 0
	v_and_b32_e32 v0, 56, v0
	s_cselect_b64 s[16:17], -1, 0
	s_add_i32 s0, s0, 0
	v_lshrrev_b32_e32 v76, 4, v73
	v_mul_u32_u24_e32 v2, 0x104, v0
	v_lshlrev_b32_e32 v3, 2, v84
	s_movk_i32 s1, 0x104
	v_add3_u32 v85, s0, v2, v3
	v_or_b32_e32 v2, 4, v76
	v_mov_b32_e32 v3, 0x410
	v_mad_u32_u24 v94, v2, s1, v3
	v_mov_b32_e32 v3, 0xc30
	v_and_b32_e32 v75, 60, v74
	v_mad_u32_u24 v95, v2, s1, v3
	v_mov_b32_e32 v3, 0x1450
	s_add_u32 s7, s4, 0x200000
	v_lshl_add_u32 v82, v75, 2, s0
	v_mad_u32_u24 v96, v2, s1, v3
	v_mov_b32_e32 v3, 0x1c70
	v_readlane_b32 s69, v255, 5
	v_readlane_b32 s70, v255, 6
	v_readlane_b32 s71, v255, 7
	v_readlane_b32 s78, v255, 14
	v_readlane_b32 s79, v255, 15
	v_readlane_b32 s80, v255, 16
	v_readlane_b32 s81, v255, 17
	v_readlane_b32 s82, v255, 18
	v_readlane_b32 s83, v255, 19
	v_writelane_b32 v255, s2, 22
	s_addc_u32 s9, s5, 0
	v_mad_u32_u24 v83, v76, s1, v82
	v_mov_b32_e32 v1, 0
	v_mad_u32_u24 v97, v2, s1, v3
	v_mov_b32_e32 v3, 0x2490
	s_lshl_b32 s0, s6, 2
	v_writelane_b32 v255, s3, 23
	v_or_b32_e32 v86, 8, v84
	v_or_b32_e32 v87, 16, v84
	v_or_b32_e32 v88, 24, v84
	v_or_b32_e32 v89, 32, v84
	v_or_b32_e32 v90, 40, v84
	v_or_b32_e32 v91, 48, v84
	v_or_b32_e32 v92, 56, v84
	v_mul_u32_u24_e32 v93, 0x104, v2
	v_mad_u32_u24 v98, v2, s1, v3
	v_mov_b32_e32 v77, v1
	s_lshl_b32 s28, s6, 6
	s_lshl_b32 s29, s8, 6
	s_lshl_b32 s30, s6, 1
	s_lshl_b32 s31, s8, 1
	s_lshl_b32 s33, s6, 3
	s_lshl_b32 s34, s8, 3
	s_add_i32 s35, s0, 0x3c600
	s_lshl_b32 s95, s8, 2
	s_mov_b32 s96, 0x8000
	s_mov_b32 s97, 0x10000
	s_mov_b32 s10, 0x18000
	s_mov_b32 s11, 0x20000
	s_mov_b32 s85, 0x28000
	s_mov_b32 s86, 0x30000
	s_mov_b32 s87, 0x38000
	s_mov_b32 s2, 0x40000
	s_mov_b32 s3, 0x48000
	s_mov_b32 s12, 0x50000
	s_mov_b32 s13, 0x58000
	s_mov_b32 s93, 0x60000
	s_mov_b32 s94, 0x68000
	s_mov_b32 s84, 0x78000
	v_add_u32_e32 v99, 0x410, v83
	v_add_u32_e32 v100, 0x418, v83
	v_add_u32_e32 v101, 0x820, v83
	v_add_u32_e32 v102, 0x828, v83
	v_add_u32_e32 v103, 0xc30, v83
	v_add_u32_e32 v104, 0xc38, v83
	v_add_u32_e32 v105, 0x1040, v83
	v_add_u32_e32 v106, 0x1048, v83
	v_add_u32_e32 v107, 0x1450, v83
	v_add_u32_e32 v108, 0x1458, v83
	v_add_u32_e32 v109, 0x1860, v83
	v_add_u32_e32 v110, 0x1868, v83
	v_add_u32_e32 v111, 0x1c70, v83
	v_add_u32_e32 v112, 0x1c78, v83
	v_add_u32_e32 v113, 0x2080, v83
	v_add_u32_e32 v114, 0x2088, v83
	v_add_u32_e32 v115, 0x2490, v83
	v_add_u32_e32 v116, 0x2498, v83
	v_add_u32_e32 v117, 0x28a0, v83
	v_add_u32_e32 v118, 0x28a8, v83
	v_add_u32_e32 v119, 0x2cb0, v83
	v_add_u32_e32 v120, 0x2cb8, v83
	v_add_u32_e32 v121, 0x30c0, v83
	v_add_u32_e32 v122, 0x30c8, v83
	v_add_u32_e32 v123, 0x34d0, v83
	v_add_u32_e32 v124, 0x34d8, v83
	v_add_u32_e32 v125, 0x38e0, v83
	v_add_u32_e32 v126, 0x38e8, v83
	v_add_u32_e32 v127, 0x3cf0, v83
	v_add_u32_e32 v128, 0x3cf8, v83
	v_mov_b32_e32 v129, 0x100
	v_mov_b32_e32 v130, 0x400
	v_mov_b32_e32 v131, 0x12140
	v_mov_b32_e32 v132, 0x24280
	v_mov_b32_e32 v133, 0x363c0
	v_mov_b32_e32 v134, 0x48500
	v_mov_b32_e32 v135, 0x5a640
	v_mov_b32_e32 v136, 0x6c780
	v_mov_b32_e32 v137, 0x7e8c0
	v_mov_b32_e32 v138, 0x90a00
	v_mov_b32_e32 v139, 0xa2b40
	v_mov_b32_e32 v140, 0xb4c80
	v_mov_b32_e32 v141, 0xc6dc0
	v_mov_b32_e32 v142, 0xd8f00
	v_mov_b32_e32 v143, 0xeb040
	v_mov_b32_e32 v144, 0xfd180
	v_mov_b32_e32 v145, 0x10f2c0
	v_lshlrev_b32_e32 v78, 1, v0
	s_movk_i32 s88, 0x4850
	s_mov_b32 s89, s6
	s_branch .LBB0_23

;     __device__ __forceinline__ bool next(int i, AB& u) const {
;         int Lx = i * G + c;
;         const char* hb = (const char*)(ws + WS_HB); const char* wt = (const char*)(ws + WS_W + (size_t)l * SZ_LAYER + OF_WIN);
;         if (Lx < 448) { int pm, pn; tile_order(Lx, 32, 14, pm, pn); u.A = hb + (size_t)pm * 256 * D_ * 2; u.B = wt + (size_t)pn * 256 * D_ * 2; return true; }
;         Lx -= 448;
;         if (Lx < 160) { const int pm = Lx % 5, pn = Lx / 5; u.A = wt + (size_t)(NP + pm * 256) * D_ * 2; u.B = hb + (size_t)pn * 256 * D_ * 2; return true; }
;         Lx -= 160;
;         if (Lx < nkv) { const int lk = Lx >> 2, j = Lx & 3; const char* w = (const char*)(ws + WS_W + OF_WKV + (size_t)lk * SZ_LAYER); const char* memb = (const char*)(ws + WS_MEMB);
;             if (j < 2) { u.A = memb; u.B = w + (size_t)j * 256 * D_ * 2; } else { u.A = w + (size_t)(512 + (j - 2) * 256) * D_ * 2; u.B = memb; }
;             return true; }
;         return false;
;     }
.LBB0_321:
	s_cmp_eq_u32 s22, 0
	v_readlane_b32 s27, v255, 0
	s_mov_b32 s28, s19
	v_mov_b32_e32 v8, v234
	s_mov_b64 s[10:11], s[50:51]
	s_cselect_b32 s26, 16, 0
	v_readlane_b32 s0, v255, 59
	s_nop 3
	s_lshl_b32 s0, s0, 9
	s_add_i32 s27, s27, s0
	s_add_u32 s29, s10, 0x1d600000
	s_mul_i32 s0, s22, 0x6500000
	s_addc_u32 s30, s11, 0
	v_writelane_b32 v255, s0, 39
	s_add_u32 s0, s10, s0
	s_addc_u32 s1, s11, 0
	s_add_u32 s31, s0, 0x200000
	s_addc_u32 s34, s1, 0
	s_cmpk_gt_i32 s27, 0x1bf
	v_readfirstlane_b32 s8, v8
	s_mov_b64 s[6:7], -1
	s_cbranch_scc0 .LBB0_328
	s_cmpk_gt_u32 s27, 0x25f
	s_cbranch_scc0 .LBB0_325
	s_add_i32 s9, s27, 0xfffffda0
	s_mov_b64 s[6:7], 0
	s_cmp_ge_u32 s9, s26
	s_mov_b64 s[2:3], 0
	s_cbranch_scc1 .LBB0_325
	s_lshr_b32 s0, s9, 2
	s_and_b32 s1, s27, 3
	s_mul_hi_u32 s2, s0, 0x6500000
	s_mul_i32 s0, s0, 0x6500000
	s_add_u32 s0, s10, s0
	s_addc_u32 s2, s11, s2
	s_add_u32 s3, s10, 0x27500000
	s_addc_u32 s4, s11, 0
	s_lshl_b32 s5, s1, 20
	s_add_u32 s0, s0, s5
	s_addc_u32 s2, s2, 0
	s_add_u32 s9, s0, 0x1f00000
	s_addc_u32 s2, s2, 0
	s_cmp_lt_u32 s1, 2
	s_cselect_b32 s1, s4, s2
	s_cselect_b32 s0, s3, s9
	s_cselect_b32 s5, s2, s4
	s_cselect_b32 s4, s9, s3
	s_mov_b64 s[2:3], -1
.LBB0_325:
	s_andn2_b64 vcc, exec, s[6:7]
	s_cbranch_vccnz .LBB0_327
	s_add_i32 s0, s27, 64
	s_and_b32 s0, s0, 0xff
	s_and_b32 s2, s0, 31
	s_lshr_b32 s0, s0, 5
	s_sub_i32 s0, 4, s0
	s_lshl_b32 s0, s0, 20
	s_add_u32 s0, s31, s0
	s_addc_u32 s1, s34, 0
	s_add_u32 s0, s0, 0xe00000
	s_addc_u32 s1, s1, 0
	s_lshl_b32 s2, s2, 20
	s_add_u32 s4, s29, s2
	s_addc_u32 s5, s30, 0
	s_mov_b64 s[2:3], -1

; template <class Epi, class Sched, bool APERM = false, bool HALFN = false>
; __device__ __forceinline__ void gemm_phase(LAS unsigned char* lds, const int tid_in, const int K, const Sched& S, const Epi& E) {
;     ...
;         const bool has_next = S.next(ui + 1, nxt);
;         const char* nA = has_next ? nxt.A : cA; const char* nB = has_next ? nxt.B : cB;
;     __device__ __forceinline__ bool next(int i, AB& u) const {
;     ...
;         return false;
.Lp1_nounit:
	s_mov_b64 s[14:15], 0
	s_branch .LBB0_345

; template <class Epi, class Sched, bool APERM = false, bool HALFN = false>
; __device__ __forceinline__ void gemm_phase(LAS unsigned char* lds, const int tid_in, const int K, const Sched& S, const Epi& E) {
;     ...
;         const bool has_next = S.next(ui + 1, nxt);
;         const char* nA = has_next ? nxt.A : cA; const char* nB = has_next ? nxt.B : cB;
;     __device__ __forceinline__ bool next(int i, AB& u) const {
;         int Lx = i * G + c;
;         const char* hb = (const char*)(ws + WS_HB); const char* wt = (const char*)(ws + WS_W + (size_t)l * SZ_LAYER + OF_WIN);
;         if (Lx < 448) { int pm, pn; tile_order(Lx, 32, 14, pm, pn); u.A = hb + (size_t)pm * 256 * D_ * 2; u.B = wt + (size_t)pn * 256 * D_ * 2; return true; }
;         Lx -= 448;
;         if (Lx < 160) { const int pm = Lx % 5, pn = Lx / 5; u.A = wt + (size_t)(NP + pm * 256) * D_ * 2; u.B = hb + (size_t)pn * 256 * D_ * 2; return true; }
;         Lx -= 160;
.LBB0_336:
	s_add_i32 s77, s18, 1
	s_mul_i32 s19, s77, s28
	s_add_i32 s19, s19, s27
	v_readlane_b32 s20, v255, 63
	s_nop 3
	s_cmp_ge_i32 s19, s20
	s_cbranch_scc1 .Lp1_nounit
	s_cmpk_gt_i32 s19, 0x1bf
	s_mov_b64 s[16:17], -1
	s_cbranch_scc0 .LBB0_343
	s_cmpk_gt_u32 s19, 0x25f
	s_cbranch_scc0 .LBB0_340
	s_add_i32 s20, s19, 0xfffffda0
	s_mov_b64 s[16:17], 0
	s_cmp_ge_i32 s20, s26
	s_mov_b64 s[14:15], 0
	s_cbranch_scc1 .LBB0_340
	s_lshr_b32 s10, s20, 2
	s_and_b32 s11, s19, 3
	s_mul_hi_u32 s12, s10, 0x6500000
	s_mul_i32 s10, s10, 0x6500000
	v_readlane_b32 s13, v255, 44
	s_add_u32 s10, s13, s10
	v_readlane_b32 s13, v255, 45
	s_addc_u32 s12, s13, s12
	s_lshl_b32 s13, s11, 20
	s_add_u32 s14, s10, s13
	s_addc_u32 s12, s12, 0
	s_cmp_lt_u32 s11, 2
	s_cselect_b32 s11, s80, s12
	s_cselect_b32 s10, s53, s14
	s_cselect_b32 s13, s12, s80
	s_cselect_b32 s12, s14, s53
	s_mov_b64 s[14:15], -1
.LBB0_340:
	s_andn2_b64 vcc, exec, s[16:17]
	s_cbranch_vccnz .LBB0_342
	s_add_i32 s10, s19, 64
	s_and_b32 s10, s10, 0xff
	s_and_b32 s12, s10, 31
	s_lshr_b32 s10, s10, 5
	s_sub_i32 s10, 4, s10
	s_lshl_b32 s10, s10, 20
	s_add_u32 s10, s31, s10
	s_addc_u32 s11, s34, 0
	s_add_u32 s10, s10, 0xe00000
	s_addc_u32 s11, s11, 0
	s_lshl_b32 s12, s12, 20
	s_add_u32 s12, s29, s12
	s_addc_u32 s13, s30, 0
	s_mov_b64 s[14:15], -1

;     __device__ __forceinline__ GU full(int i) const {
;     ...
;         if (Lx < 160) { const int pm = Lx % 5, pn = Lx / 5;
;             u.out = (bf16_t*)(ws + WS_VT) + (size_t)pm * 256 * T_ + pn * 256; u.sc = ssq + pn * 256; u.gates = nullptr; u.ldc = T_; u.mode = 2; return u; }
.LBB0_356:
	s_mov_b64 s[24:25], 0
	s_mov_b64 s[0:1], 0
	s_andn2_b64 vcc, exec, s[4:5]
	s_mov_b64 s[4:5], 0
	s_cbranch_vccnz .LBB0_358
	s_add_i32 s4, s44, 64
	s_and_b32 s4, s4, 0xff
	s_and_b32 s5, s4, 31
	s_lshr_b32 s4, s4, 5
	s_sub_i32 s4, 4, s4
	s_lshl_b32 s4, s4, 22
	s_add_u32 s4, s75, s4
	s_addc_u32 s17, s76, 0
	s_lshl_b32 s16, s5, 9
	s_add_u32 s16, s4, s16
	s_addc_u32 s17, s17, 0
	s_lshl_b32 s4, s5, 11
	s_add_u32 s24, s81, s4
	s_addc_u32 s25, s86, 0
	s_mov_b64 s[18:19], 0x2000
	s_mov_b64 s[4:5], -1

; #define LAS __attribute__((address_space(3)))
; #define PG8_WAIT_V(n) asm volatile("s_waitcnt vmcnt(" #n ")" ::: "memory")
; #define PG8_BAR __builtin_amdgcn_s_barrier()
; __device__ __forceinline__ unsigned xb_xcc_id() { return (unsigned)__builtin_amdgcn_s_getreg((3 << 11) | 20) & 0xFu; }
; template <class Epi, class Sched, bool APERM = false, bool HALFN = false>
; __device__ __forceinline__ void gemm_phase(LAS unsigned char* lds, const int tid_in, const int K, const Sched& S, const Epi& E) {
;     ...
;     PG8_WAIT_V(0);
;     PG8_BAR;
; __device__ __forceinline__ void xcd_barrier(unsigned* bar, volatile LAS unsigned* st, bool leader, unsigned G) {
;     asm volatile("s_waitcnt vmcnt(0)" ::: "memory");
;     __syncthreads();
;     if (leader) {
;         const unsigned x = xb_xcc_id();
;         __builtin_amdgcn_s_waitcnt(0);
;         unsigned nloc = st[0], nx = st[1];
;         if (nloc == 0u) { xcd_barrier_complete(bar, x, G, nloc, nx); st[0] = nloc; st[1] = nx; }
.LBB0_390:
	s_waitcnt vmcnt(0)
	v_readlane_b32 s0, v255, 59
	s_nop 3
	s_cmp_eq_u32 s0, 0
	s_cbranch_scc1 .Lp1_done_normal
	s_mov_b32 s0, 0
	s_nop 0
	v_writelane_b32 v255, s0, 59
	s_movk_i32 s0, 0x200
	s_nop 0
	v_writelane_b32 v255, s0, 63
	s_lshl_b32 s20, s22, 2
	s_lshl_b32 s38, s22, 8
	s_lshl_b32 s0, s22, 14
	s_add_u32 s57, s64, s0
	s_addc_u32 s95, s65, 0
	s_branch .LBB0_481
.Lp1_done_normal:
	s_waitcnt vmcnt(0) lgkmcnt(0)
	s_barrier
	s_mov_b64 s[0:1], exec
	v_readlane_b32 s2, v255, 24
	v_readlane_b32 s3, v255, 25
	s_and_b64 s[2:3], s[0:1], s[2:3]
	s_mov_b64 exec, s[2:3]
	s_cbranch_execz .LBB0_442
	v_readlane_b32 s3, v255, 34
	s_getreg_b32 s2, hwreg(HW_REG_XCC_ID, 0, 4)
	s_waitcnt vmcnt(0) expcnt(0) lgkmcnt(0)
	v_mov_b32_e32 v0, s3
	ds_read_b32 v2, v0
	v_readlane_b32 s3, v255, 35
	s_and_b32 s8, s2, 15
	s_waitcnt lgkmcnt(0)
	v_cmp_ne_u32_e32 vcc, 0, v2
	v_mov_b32_e32 v0, s3
	ds_read_b32 v0, v0
	s_cbranch_vccnz .LBB0_406
	s_mov_b32 s9, 1
	s_branch .LBB0_394

; #define LAS __attribute__((address_space(3)))
; __device__ __forceinline__ float logsig(float x) { return fminf(x, 0.f) - __logf(1.f + __expf(-fabsf(x))); }
; #define REPS(k) for (int rep_ = 0; rep_ < (((RPM) >> (k)) & 1) + 1; ++rep_)
; __global__ void __launch_bounds__(512, 2) hybrid_fwd(Params p) {
;     ...
;         if (PH(2)) REPS(2) { PHB
;             for (int u = c; u < 4 + 512 + 64; u += G) {
;                 if (u < 4) {
;                     const int hd = u; const float bf = p.b_fox_f[l * 4 + hd];
;                     LAS float* wt = (LAS float*)lds;
;                     float pre[16]; float run = 0.f;
; #pragma unroll
;                     for (int j = 0; j < 16; ++j) { run += logsig(GATES[(size_t)(tid * 16 + j) * 32 + hd] + bf); pre[j] = run; }
;                     float xs = run;
; #pragma unroll
;                     for (int off = 1; off < 64; off <<= 1) { const float y = __int_as_float(__builtin_amdgcn_ds_bpermute((lane >= off ? lane - off : lane) << 2, __float_as_int(xs))); if (lane >= off) xs += y; }
;                     if (lane == 63) wt[wave] = xs;
.LBB0_442:
	s_or_b64 exec, exec, s[0:1]
	s_lshl_b32 s0, s22, 14
	s_add_u32 s57, s64, s0
	v_readlane_b32 s0, v255, 0
	s_addc_u32 s95, s65, 0
	s_lshl_b32 s38, s22, 8
	s_lshl_b32 s20, s22, 2
	s_mov_b32 s2, s0
	s_mov_b32 s34, s19
	v_mov_b32_e32 v52, v234
	s_waitcnt lgkmcnt(0)
	s_barrier
	v_readlane_b32 s0, v255, 58
	s_nop 3
	s_cmp_eq_u32 s0, 0
	s_cbranch_scc1 .Lp2_go
	s_movk_i32 s3, 0x60
	s_cmp_eq_u32 s22, 0
	s_cselect_b32 s3, 0x70, s3
	s_cmp_ge_u32 s2, s3
	s_cbranch_scc1 .Lp2_light
	s_mov_b32 s0, 1
	s_nop 0
	v_writelane_b32 v255, s0, 59
	s_mov_b32 s0, 0x7fffffff
	s_nop 0
	v_writelane_b32 v255, s0, 63
	s_branch .LBB0_321
.Lp2_light:
	s_sub_u32 s2, s2, s3
	s_sub_u32 s34, s34, s3
.Lp2_go:
	s_mov_b64 s[18:19], s[50:51]
	v_readfirstlane_b32 s0, v52
	s_cmpk_lt_i32 s2, 0x244
	s_cbranch_scc0 .LBB0_481
	s_mov_b32 s21, s73
	s_ashr_i32 s3, s0, 6
	s_lshl_b64 s[4:5], s[20:21], 2
	s_add_u32 s4, s18, s4
	s_addc_u32 s5, s19, s5
	v_and_b32_e32 v4, 63, v52
	s_add_u32 s4, s4, 0x38f80000
	v_lshlrev_b32_e32 v0, 2, v4
	v_writelane_b32 v255, s4, 45
	s_addc_u32 s4, s5, 0
	v_xor_b32_e32 v54, 4, v0
	v_xor_b32_e32 v55, 8, v0
	v_xor_b32_e32 v56, 16, v0
	v_xor_b32_e32 v57, 32, v0
	v_xor_b32_e32 v58, 64, v0
	v_xor_b32_e32 v59, 0x80, v0
	s_add_u32 s39, s18, 0x22e00000
	v_lshlrev_b32_e32 v0, 4, v52
	v_writelane_b32 v255, s4, 44
	s_addc_u32 s76, s19, 0
	s_lshl_b32 s4, s3, 2
	v_ashrrev_i32_e32 v1, 31, v0
	s_add_i32 s77, s4, 0
	v_lshl_add_u64 v[2:3], v[0:1], 2, s[18:19]
	s_mov_b64 s[4:5], 0x38f00000
	v_lshl_add_u64 v[16:17], v[2:3], 0, s[4:5]
	v_or_b32_e32 v2, 1, v0
	v_ashrrev_i32_e32 v3, 31, v2
	v_lshlrev_b64 v[20:21], 7, v[2:3]
	v_or_b32_e32 v2, 2, v0
	v_ashrrev_i32_e32 v3, 31, v2
	v_lshlrev_b64 v[22:23], 7, v[2:3]
	v_or_b32_e32 v2, 3, v0
	v_ashrrev_i32_e32 v3, 31, v2
	v_lshlrev_b64 v[24:25], 7, v[2:3]
	v_or_b32_e32 v2, 4, v0
	v_ashrrev_i32_e32 v3, 31, v2
	v_lshlrev_b64 v[26:27], 7, v[2:3]
	v_or_b32_e32 v2, 5, v0
	v_ashrrev_i32_e32 v3, 31, v2
	v_lshlrev_b64 v[28:29], 7, v[2:3]
	v_or_b32_e32 v2, 6, v0
	v_ashrrev_i32_e32 v3, 31, v2
	v_lshlrev_b64 v[30:31], 7, v[2:3]
	v_or_b32_e32 v2, 7, v0
	v_ashrrev_i32_e32 v3, 31, v2
	v_lshlrev_b64 v[32:33], 7, v[2:3]
	v_or_b32_e32 v2, 8, v0
	v_ashrrev_i32_e32 v3, 31, v2
	v_lshlrev_b64 v[34:35], 7, v[2:3]
	v_or_b32_e32 v2, 9, v0
	v_ashrrev_i32_e32 v3, 31, v2
	v_lshlrev_b64 v[36:37], 7, v[2:3]
	v_or_b32_e32 v2, 10, v0
	v_ashrrev_i32_e32 v3, 31, v2
	v_lshlrev_b64 v[38:39], 7, v[2:3]
	v_or_b32_e32 v2, 11, v0
	v_ashrrev_i32_e32 v3, 31, v2
	v_lshlrev_b64 v[40:41], 7, v[2:3]
	v_or_b32_e32 v2, 12, v0
	v_ashrrev_i32_e32 v3, 31, v2
	v_lshlrev_b64 v[42:43], 7, v[2:3]
	v_or_b32_e32 v2, 13, v0
	v_ashrrev_i32_e32 v3, 31, v2
	v_lshlrev_b64 v[18:19], 7, v[0:1]
	v_lshlrev_b64 v[44:45], 7, v[2:3]
	v_or_b32_e32 v2, 14, v0
	v_or_b32_e32 v0, 15, v0
	v_ashrrev_i32_e32 v1, 31, v0
	v_cmp_ne_u32_e64 s[4:5], 0, v4
	v_lshlrev_b64 v[48:49], 7, v[0:1]
	v_cmp_gt_u32_e64 s[6:7], 2, v4
	v_subbrev_co_u32_e64 v0, vcc, 0, v4, s[4:5]
	s_cmp_gt_i32 s3, 0
	v_lshlrev_b32_e32 v60, 2, v0
	v_cndmask_b32_e64 v0, -2, 0, s[6:7]
	v_cmp_gt_u32_e64 s[8:9], 4, v4
	s_cselect_b64 s[22:23], -1, 0
	s_cmp_gt_i32 s3, 1
	v_add_lshl_u32 v61, v0, v4, 2
	v_cndmask_b32_e64 v0, -4, 0, s[8:9]
	v_cmp_gt_u32_e64 s[10:11], 8, v4
	s_cselect_b64 s[24:25], -1, 0
	s_cmp_gt_i32 s3, 2
	v_add_lshl_u32 v62, v0, v4, 2
	v_cndmask_b32_e64 v0, -8, 0, s[10:11]
	v_cmp_gt_u32_e64 s[12:13], 16, v4
	s_cselect_b64 s[26:27], -1, 0
	s_cmp_gt_i32 s3, 3
	v_add_lshl_u32 v63, v0, v4, 2
	v_cndmask_b32_e64 v0, -16, 0, s[12:13]
	s_cselect_b64 s[28:29], -1, 0
	s_cmp_gt_i32 s3, 4
	v_add_lshl_u32 v64, v0, v4, 2
	v_lshlrev_b32_e32 v0, 2, v52
	s_cselect_b64 s[30:31], -1, 0
	s_cmp_gt_i32 s3, 5
	v_and_b32_e32 v65, 0x7c, v0
	s_cselect_b64 s[70:71], -1, 0
	s_cmp_gt_i32 s3, 6
	v_and_b32_e32 v0, 15, v52
	s_cselect_b64 s[92:93], -1, 0
	s_cmp_gt_i32 s3, 7
	v_lshlrev_b32_e32 v200, 4, v0
	v_ashrrev_i32_e32 v53, 4, v52
	v_ashrrev_i32_e32 v3, 31, v2
	s_cselect_b64 s[80:81], -1, 0
	v_lshl_add_u64 v[0:1], s[18:19], 0, v[200:201]
	s_mov_b64 s[18:19], 0x1f600400
	s_lshl_b32 s3, s2, 9
	v_cmp_eq_u32_e64 s[0:1], 0, v4
	v_cmp_eq_u32_e64 s[16:17], 63, v4
	v_lshlrev_b64 v[46:47], 7, v[2:3]
	v_cmp_gt_u32_e64 s[14:15], 32, v4
	v_lshl_add_u64 v[50:51], v[0:1], 0, s[18:19]
	v_add_u32_e32 v66, 0x60, v53
	s_add_i32 s86, s3, 0xfffbf800
	s_lshl_b32 s87, s34, 9
	s_add_i32 s21, s2, 0xfffffdfc
	v_add_u32_e32 v67, 64, v53
	v_add_u32_e32 v68, 32, v53
	s_branch .LBB0_446
